# accumulator clearing at each GEMM tile start with 64-bit moves (65 instead of 128 VALU instructions per tile)
# speedup vs baseline: 1.0057x; 1.0057x over previous
.LBB0_144:
	s_add_u32 s24, s24, 0x40080
	s_addc_u32 s25, s25, 0
	s_add_u32 s11, s26, 0x100
	v_mov_b32_e32 v0, 0
	v_mov_b32_e32 v1, 0
	v_mov_b64_e32 v[2:3], 0
	v_mov_b64_e32 v[4:5], 0
	v_mov_b64_e32 v[6:7], 0
	v_mov_b64_e32 v[8:9], 0
	v_mov_b64_e32 v[10:11], 0
	v_mov_b64_e32 v[12:13], 0
	v_mov_b64_e32 v[14:15], 0
	v_mov_b64_e32 v[16:17], 0
	v_mov_b64_e32 v[18:19], 0
	v_mov_b64_e32 v[20:21], 0
	v_mov_b64_e32 v[22:23], 0
	v_mov_b64_e32 v[24:25], 0
	v_mov_b64_e32 v[26:27], 0
	v_mov_b64_e32 v[28:29], 0
	v_mov_b64_e32 v[30:31], 0
	v_mov_b64_e32 v[32:33], 0
	v_mov_b64_e32 v[34:35], 0
	v_mov_b64_e32 v[36:37], 0
	v_mov_b64_e32 v[38:39], 0
	v_mov_b64_e32 v[40:41], 0
	v_mov_b64_e32 v[42:43], 0
	v_mov_b64_e32 v[44:45], 0
	v_mov_b64_e32 v[46:47], 0
	v_mov_b64_e32 v[48:49], 0
	v_mov_b64_e32 v[50:51], 0
	v_mov_b64_e32 v[52:53], 0
	v_mov_b64_e32 v[54:55], 0
	v_mov_b64_e32 v[56:57], 0
	v_mov_b64_e32 v[58:59], 0
	v_mov_b64_e32 v[60:61], 0
	v_mov_b64_e32 v[62:63], 0
	v_mov_b64_e32 v[64:65], 0
	v_mov_b64_e32 v[66:67], 0
	v_mov_b64_e32 v[68:69], 0
	v_mov_b64_e32 v[70:71], 0
	v_mov_b64_e32 v[72:73], 0
	v_mov_b64_e32 v[74:75], 0
	v_mov_b64_e32 v[76:77], 0
	v_mov_b64_e32 v[78:79], 0
	v_mov_b64_e32 v[80:81], 0
	v_mov_b64_e32 v[82:83], 0
	v_mov_b64_e32 v[84:85], 0
	v_mov_b64_e32 v[86:87], 0
	v_mov_b64_e32 v[88:89], 0
	v_mov_b64_e32 v[90:91], 0
	v_mov_b64_e32 v[92:93], 0
	v_mov_b64_e32 v[94:95], 0
	v_mov_b64_e32 v[96:97], 0
	v_mov_b64_e32 v[98:99], 0
	v_mov_b64_e32 v[100:101], 0
	v_mov_b64_e32 v[102:103], 0
	v_mov_b64_e32 v[104:105], 0
	v_mov_b64_e32 v[106:107], 0
	v_mov_b64_e32 v[108:109], 0
	v_mov_b64_e32 v[110:111], 0
	v_mov_b64_e32 v[112:113], 0
	v_mov_b64_e32 v[114:115], 0
	v_mov_b64_e32 v[116:117], 0
	v_mov_b64_e32 v[118:119], 0
	v_mov_b64_e32 v[120:121], 0
	v_mov_b64_e32 v[122:123], 0
	v_mov_b64_e32 v[124:125], 0
	v_mov_b64_e32 v[126:127], 0
	s_addc_u32 s13, s27, 0
	s_mov_b32 s23, -2

.LBB0_219:
	s_add_u32 s24, s24, 0x40080
	s_addc_u32 s25, s25, 0
	s_add_u32 s13, s26, 0x100
	v_mov_b32_e32 v0, 0
	v_mov_b32_e32 v1, 0
	v_mov_b64_e32 v[2:3], 0
	v_mov_b64_e32 v[4:5], 0
	v_mov_b64_e32 v[6:7], 0
	v_mov_b64_e32 v[8:9], 0
	v_mov_b64_e32 v[10:11], 0
	v_mov_b64_e32 v[12:13], 0
	v_mov_b64_e32 v[14:15], 0
	v_mov_b64_e32 v[16:17], 0
	v_mov_b64_e32 v[18:19], 0
	v_mov_b64_e32 v[20:21], 0
	v_mov_b64_e32 v[22:23], 0
	v_mov_b64_e32 v[24:25], 0
	v_mov_b64_e32 v[26:27], 0
	v_mov_b64_e32 v[28:29], 0
	v_mov_b64_e32 v[30:31], 0
	v_mov_b64_e32 v[32:33], 0
	v_mov_b64_e32 v[34:35], 0
	v_mov_b64_e32 v[36:37], 0
	v_mov_b64_e32 v[38:39], 0
	v_mov_b64_e32 v[40:41], 0
	v_mov_b64_e32 v[42:43], 0
	v_mov_b64_e32 v[44:45], 0
	v_mov_b64_e32 v[46:47], 0
	v_mov_b64_e32 v[48:49], 0
	v_mov_b64_e32 v[50:51], 0
	v_mov_b64_e32 v[52:53], 0
	v_mov_b64_e32 v[54:55], 0
	v_mov_b64_e32 v[56:57], 0
	v_mov_b64_e32 v[58:59], 0
	v_mov_b64_e32 v[60:61], 0
	v_mov_b64_e32 v[62:63], 0
	v_mov_b64_e32 v[64:65], 0
	v_mov_b64_e32 v[66:67], 0
	v_mov_b64_e32 v[68:69], 0
	v_mov_b64_e32 v[70:71], 0
	v_mov_b64_e32 v[72:73], 0
	v_mov_b64_e32 v[74:75], 0
	v_mov_b64_e32 v[76:77], 0
	v_mov_b64_e32 v[78:79], 0
	v_mov_b64_e32 v[80:81], 0
	v_mov_b64_e32 v[82:83], 0
	v_mov_b64_e32 v[84:85], 0
	v_mov_b64_e32 v[86:87], 0
	v_mov_b64_e32 v[88:89], 0
	v_mov_b64_e32 v[90:91], 0
	v_mov_b64_e32 v[92:93], 0
	v_mov_b64_e32 v[94:95], 0
	v_mov_b64_e32 v[96:97], 0
	v_mov_b64_e32 v[98:99], 0
	v_mov_b64_e32 v[100:101], 0
	v_mov_b64_e32 v[102:103], 0
	v_mov_b64_e32 v[104:105], 0
	v_mov_b64_e32 v[106:107], 0
	v_mov_b64_e32 v[108:109], 0
	v_mov_b64_e32 v[110:111], 0
	v_mov_b64_e32 v[112:113], 0
	v_mov_b64_e32 v[114:115], 0
	v_mov_b64_e32 v[116:117], 0
	v_mov_b64_e32 v[118:119], 0
	v_mov_b64_e32 v[120:121], 0
	v_mov_b64_e32 v[122:123], 0
	v_mov_b64_e32 v[124:125], 0
	v_mov_b64_e32 v[126:127], 0
	s_addc_u32 s15, s27, 0
	s_mov_b32 s47, -2

.LBB0_322:
	v_mov_b32_e32 v127, 0
	s_and_b64 vcc, exec, s[0:1]
	v_mov_b32_e32 v126, v127
	v_mov_b32_e32 v125, v127
	v_mov_b32_e32 v124, v127
	v_mov_b32_e32 v123, v127
	v_mov_b32_e32 v122, v127
	v_mov_b32_e32 v121, v127
	v_mov_b32_e32 v120, v127
	v_mov_b32_e32 v111, v127
	v_mov_b32_e32 v110, v127
	v_mov_b32_e32 v109, v127
	v_mov_b32_e32 v108, v127
	v_mov_b32_e32 v107, v127
	v_mov_b32_e32 v106, v127
	v_mov_b32_e32 v105, v127
	v_mov_b32_e32 v104, v127
	v_mov_b32_e32 v95, v127
	v_mov_b32_e32 v94, v127
	v_mov_b32_e32 v93, v127
	v_mov_b32_e32 v92, v127
	v_mov_b32_e32 v91, v127
	v_mov_b32_e32 v90, v127
	v_mov_b32_e32 v89, v127
	v_mov_b32_e32 v88, v127
	v_mov_b32_e32 v79, v127
	v_mov_b32_e32 v78, v127
	v_mov_b32_e32 v77, v127
	v_mov_b32_e32 v76, v127
	v_mov_b32_e32 v75, v127
	v_mov_b32_e32 v74, v127
	v_mov_b32_e32 v73, v127
	v_mov_b32_e32 v72, v127
	v_mov_b32_e32 v119, v127
	v_mov_b32_e32 v118, v127
	v_mov_b32_e32 v117, v127
	v_mov_b32_e32 v116, v127
	v_mov_b32_e32 v115, v127
	v_mov_b32_e32 v114, v127
	v_mov_b32_e32 v113, v127
	v_mov_b32_e32 v112, v127
	v_mov_b32_e32 v103, v127
	v_mov_b32_e32 v102, v127
	v_mov_b32_e32 v101, v127
	v_mov_b32_e32 v100, v127
	v_mov_b32_e32 v99, v127
	v_mov_b32_e32 v98, v127
	v_mov_b32_e32 v97, v127
	v_mov_b32_e32 v96, v127
	v_mov_b32_e32 v87, v127
	v_mov_b32_e32 v86, v127
	v_mov_b32_e32 v85, v127
	v_mov_b32_e32 v84, v127
	v_mov_b32_e32 v83, v127
	v_mov_b32_e32 v82, v127
	v_mov_b32_e32 v81, v127
	v_mov_b32_e32 v80, v127
	v_mov_b32_e32 v71, v127
	v_mov_b32_e32 v70, v127
	v_mov_b32_e32 v69, v127
	v_mov_b32_e32 v68, v127
	v_mov_b32_e32 v67, v127
	v_mov_b32_e32 v66, v127
	v_mov_b32_e32 v65, v127
	v_mov_b32_e32 v64, v127
	v_mov_b32_e32 v63, v127
	v_mov_b32_e32 v62, v127
	v_mov_b32_e32 v61, v127
	v_mov_b32_e32 v60, v127
	v_mov_b32_e32 v59, v127
	v_mov_b32_e32 v58, v127
	v_mov_b32_e32 v57, v127
	v_mov_b32_e32 v56, v127
	v_mov_b32_e32 v47, v127
	v_mov_b32_e32 v46, v127
	v_mov_b32_e32 v45, v127
	v_mov_b32_e32 v44, v127
	v_mov_b32_e32 v43, v127
	v_mov_b32_e32 v42, v127
	v_mov_b32_e32 v41, v127
	v_mov_b32_e32 v40, v127
	v_mov_b32_e32 v31, v127
	v_mov_b32_e32 v30, v127
	v_mov_b32_e32 v29, v127
	v_mov_b32_e32 v28, v127
	v_mov_b32_e32 v27, v127
	v_mov_b32_e32 v26, v127
	v_mov_b32_e32 v25, v127
	v_mov_b32_e32 v24, v127
	v_mov_b32_e32 v15, v127
	v_mov_b32_e32 v14, v127
	v_mov_b32_e32 v13, v127
	v_mov_b32_e32 v12, v127
	v_mov_b32_e32 v11, v127
	v_mov_b32_e32 v10, v127
	v_mov_b32_e32 v9, v127
	v_mov_b32_e32 v8, v127
	v_mov_b32_e32 v55, v127
	v_mov_b32_e32 v54, v127
	v_mov_b32_e32 v53, v127
	v_mov_b32_e32 v52, v127
	v_mov_b32_e32 v51, v127
	v_mov_b32_e32 v50, v127
	v_mov_b32_e32 v49, v127
	v_mov_b32_e32 v48, v127
	v_mov_b32_e32 v39, v127
	v_mov_b32_e32 v38, v127
	v_mov_b32_e32 v37, v127
	v_mov_b32_e32 v36, v127
	v_mov_b32_e32 v35, v127
	v_mov_b32_e32 v34, v127
	v_mov_b32_e32 v33, v127
	v_mov_b32_e32 v32, v127
	v_mov_b32_e32 v23, v127
	v_mov_b32_e32 v22, v127
	v_mov_b32_e32 v21, v127
	v_mov_b32_e32 v20, v127
	v_mov_b32_e32 v19, v127
	v_mov_b32_e32 v18, v127
	v_mov_b32_e32 v17, v127
	v_mov_b32_e32 v16, v127
	v_mov_b32_e32 v7, v127
	v_mov_b32_e32 v6, v127
	v_mov_b32_e32 v5, v127
	v_mov_b32_e32 v4, v127
	v_mov_b32_e32 v3, v127
	v_mov_b32_e32 v2, v127
	v_mov_b32_e32 v1, v127
	v_mov_b32_e32 v0, v127
	s_cbranch_vccnz .LBB0_325
	s_add_u32 s28, s28, 0x80080
	s_addc_u32 s29, s29, 0
	s_add_u32 s53, s30, 0x100
	v_mov_b32_e32 v0, 0
	v_mov_b32_e32 v1, 0
	v_mov_b64_e32 v[2:3], 0
	v_mov_b64_e32 v[4:5], 0
	v_mov_b64_e32 v[6:7], 0
	v_mov_b64_e32 v[8:9], 0
	v_mov_b64_e32 v[10:11], 0
	v_mov_b64_e32 v[12:13], 0
	v_mov_b64_e32 v[14:15], 0
	v_mov_b64_e32 v[16:17], 0
	v_mov_b64_e32 v[18:19], 0
	v_mov_b64_e32 v[20:21], 0
	v_mov_b64_e32 v[22:23], 0
	v_mov_b64_e32 v[24:25], 0
	v_mov_b64_e32 v[26:27], 0
	v_mov_b64_e32 v[28:29], 0
	v_mov_b64_e32 v[30:31], 0
	v_mov_b64_e32 v[32:33], 0
	v_mov_b64_e32 v[34:35], 0
	v_mov_b64_e32 v[36:37], 0
	v_mov_b64_e32 v[38:39], 0
	v_mov_b64_e32 v[40:41], 0
	v_mov_b64_e32 v[42:43], 0
	v_mov_b64_e32 v[44:45], 0
	v_mov_b64_e32 v[46:47], 0
	v_mov_b64_e32 v[48:49], 0
	v_mov_b64_e32 v[50:51], 0
	v_mov_b64_e32 v[52:53], 0
	v_mov_b64_e32 v[54:55], 0
	v_mov_b64_e32 v[56:57], 0
	v_mov_b64_e32 v[58:59], 0
	v_mov_b64_e32 v[60:61], 0
	v_mov_b64_e32 v[62:63], 0
	v_mov_b64_e32 v[64:65], 0
	v_mov_b64_e32 v[66:67], 0
	v_mov_b64_e32 v[68:69], 0
	v_mov_b64_e32 v[70:71], 0
	v_mov_b64_e32 v[72:73], 0
	v_mov_b64_e32 v[74:75], 0
	v_mov_b64_e32 v[76:77], 0
	v_mov_b64_e32 v[78:79], 0
	v_mov_b64_e32 v[80:81], 0
	v_mov_b64_e32 v[82:83], 0
	v_mov_b64_e32 v[84:85], 0
	v_mov_b64_e32 v[86:87], 0
	v_mov_b64_e32 v[88:89], 0
	v_mov_b64_e32 v[90:91], 0
	v_mov_b64_e32 v[92:93], 0
	v_mov_b64_e32 v[94:95], 0
	v_mov_b64_e32 v[96:97], 0
	v_mov_b64_e32 v[98:99], 0
	v_mov_b64_e32 v[100:101], 0
	v_mov_b64_e32 v[102:103], 0
	v_mov_b64_e32 v[104:105], 0
	v_mov_b64_e32 v[106:107], 0
	v_mov_b64_e32 v[108:109], 0
	v_mov_b64_e32 v[110:111], 0
	v_mov_b64_e32 v[112:113], 0
	v_mov_b64_e32 v[114:115], 0
	v_mov_b64_e32 v[116:117], 0
	v_mov_b64_e32 v[118:119], 0
	v_mov_b64_e32 v[120:121], 0
	v_mov_b64_e32 v[122:123], 0
	v_mov_b64_e32 v[124:125], 0
	v_mov_b64_e32 v[126:127], 0
	s_addc_u32 s54, s31, 0
	s_mov_b32 s30, 0

.LBB0_339:
	v_mov_b32_e32 v127, 0
	s_and_b64 vcc, exec, s[0:1]
	v_mov_b32_e32 v126, v127
	v_mov_b32_e32 v125, v127
	v_mov_b32_e32 v124, v127
	v_mov_b32_e32 v123, v127
	v_mov_b32_e32 v122, v127
	v_mov_b32_e32 v121, v127
	v_mov_b32_e32 v120, v127
	v_mov_b32_e32 v111, v127
	v_mov_b32_e32 v110, v127
	v_mov_b32_e32 v109, v127
	v_mov_b32_e32 v108, v127
	v_mov_b32_e32 v107, v127
	v_mov_b32_e32 v106, v127
	v_mov_b32_e32 v105, v127
	v_mov_b32_e32 v104, v127
	v_mov_b32_e32 v95, v127
	v_mov_b32_e32 v94, v127
	v_mov_b32_e32 v93, v127
	v_mov_b32_e32 v92, v127
	v_mov_b32_e32 v91, v127
	v_mov_b32_e32 v90, v127
	v_mov_b32_e32 v89, v127
	v_mov_b32_e32 v88, v127
	v_mov_b32_e32 v79, v127
	v_mov_b32_e32 v78, v127
	v_mov_b32_e32 v77, v127
	v_mov_b32_e32 v76, v127
	v_mov_b32_e32 v75, v127
	v_mov_b32_e32 v74, v127
	v_mov_b32_e32 v73, v127
	v_mov_b32_e32 v72, v127
	v_mov_b32_e32 v119, v127
	v_mov_b32_e32 v118, v127
	v_mov_b32_e32 v117, v127
	v_mov_b32_e32 v116, v127
	v_mov_b32_e32 v115, v127
	v_mov_b32_e32 v114, v127
	v_mov_b32_e32 v113, v127
	v_mov_b32_e32 v112, v127
	v_mov_b32_e32 v103, v127
	v_mov_b32_e32 v102, v127
	v_mov_b32_e32 v101, v127
	v_mov_b32_e32 v100, v127
	v_mov_b32_e32 v99, v127
	v_mov_b32_e32 v98, v127
	v_mov_b32_e32 v97, v127
	v_mov_b32_e32 v96, v127
	v_mov_b32_e32 v87, v127
	v_mov_b32_e32 v86, v127
	v_mov_b32_e32 v85, v127
	v_mov_b32_e32 v84, v127
	v_mov_b32_e32 v83, v127
	v_mov_b32_e32 v82, v127
	v_mov_b32_e32 v81, v127
	v_mov_b32_e32 v80, v127
	v_mov_b32_e32 v71, v127
	v_mov_b32_e32 v70, v127
	v_mov_b32_e32 v69, v127
	v_mov_b32_e32 v68, v127
	v_mov_b32_e32 v67, v127
	v_mov_b32_e32 v66, v127
	v_mov_b32_e32 v65, v127
	v_mov_b32_e32 v64, v127
	v_mov_b32_e32 v63, v127
	v_mov_b32_e32 v62, v127
	v_mov_b32_e32 v61, v127
	v_mov_b32_e32 v60, v127
	v_mov_b32_e32 v59, v127
	v_mov_b32_e32 v58, v127
	v_mov_b32_e32 v57, v127
	v_mov_b32_e32 v56, v127
	v_mov_b32_e32 v47, v127
	v_mov_b32_e32 v46, v127
	v_mov_b32_e32 v45, v127
	v_mov_b32_e32 v44, v127
	v_mov_b32_e32 v43, v127
	v_mov_b32_e32 v42, v127
	v_mov_b32_e32 v41, v127
	v_mov_b32_e32 v40, v127
	v_mov_b32_e32 v31, v127
	v_mov_b32_e32 v30, v127
	v_mov_b32_e32 v29, v127
	v_mov_b32_e32 v28, v127
	v_mov_b32_e32 v27, v127
	v_mov_b32_e32 v26, v127
	v_mov_b32_e32 v25, v127
	v_mov_b32_e32 v24, v127
	v_mov_b32_e32 v15, v127
	v_mov_b32_e32 v14, v127
	v_mov_b32_e32 v13, v127
	v_mov_b32_e32 v12, v127
	v_mov_b32_e32 v11, v127
	v_mov_b32_e32 v10, v127
	v_mov_b32_e32 v9, v127
	v_mov_b32_e32 v8, v127
	v_mov_b32_e32 v55, v127
	v_mov_b32_e32 v54, v127
	v_mov_b32_e32 v53, v127
	v_mov_b32_e32 v52, v127
	v_mov_b32_e32 v51, v127
	v_mov_b32_e32 v50, v127
	v_mov_b32_e32 v49, v127
	v_mov_b32_e32 v48, v127
	v_mov_b32_e32 v39, v127
	v_mov_b32_e32 v38, v127
	v_mov_b32_e32 v37, v127
	v_mov_b32_e32 v36, v127
	v_mov_b32_e32 v35, v127
	v_mov_b32_e32 v34, v127
	v_mov_b32_e32 v33, v127
	v_mov_b32_e32 v32, v127
	v_mov_b32_e32 v23, v127
	v_mov_b32_e32 v22, v127
	v_mov_b32_e32 v21, v127
	v_mov_b32_e32 v20, v127
	v_mov_b32_e32 v19, v127
	v_mov_b32_e32 v18, v127
	v_mov_b32_e32 v17, v127
	v_mov_b32_e32 v16, v127
	v_mov_b32_e32 v7, v127
	v_mov_b32_e32 v6, v127
	v_mov_b32_e32 v5, v127
	v_mov_b32_e32 v4, v127
	v_mov_b32_e32 v3, v127
	v_mov_b32_e32 v2, v127
	v_mov_b32_e32 v1, v127
	v_mov_b32_e32 v0, v127
	s_cbranch_vccnz .LBB0_342
	s_add_u32 s28, s28, 0x40080
	s_addc_u32 s29, s29, 0
	s_add_u32 s53, s30, 0x100
	v_mov_b32_e32 v0, 0
	v_mov_b32_e32 v1, 0
	v_mov_b64_e32 v[2:3], 0
	v_mov_b64_e32 v[4:5], 0
	v_mov_b64_e32 v[6:7], 0
	v_mov_b64_e32 v[8:9], 0
	v_mov_b64_e32 v[10:11], 0
	v_mov_b64_e32 v[12:13], 0
	v_mov_b64_e32 v[14:15], 0
	v_mov_b64_e32 v[16:17], 0
	v_mov_b64_e32 v[18:19], 0
	v_mov_b64_e32 v[20:21], 0
	v_mov_b64_e32 v[22:23], 0
	v_mov_b64_e32 v[24:25], 0
	v_mov_b64_e32 v[26:27], 0
	v_mov_b64_e32 v[28:29], 0
	v_mov_b64_e32 v[30:31], 0
	v_mov_b64_e32 v[32:33], 0
	v_mov_b64_e32 v[34:35], 0
	v_mov_b64_e32 v[36:37], 0
	v_mov_b64_e32 v[38:39], 0
	v_mov_b64_e32 v[40:41], 0
	v_mov_b64_e32 v[42:43], 0
	v_mov_b64_e32 v[44:45], 0
	v_mov_b64_e32 v[46:47], 0
	v_mov_b64_e32 v[48:49], 0
	v_mov_b64_e32 v[50:51], 0
	v_mov_b64_e32 v[52:53], 0
	v_mov_b64_e32 v[54:55], 0
	v_mov_b64_e32 v[56:57], 0
	v_mov_b64_e32 v[58:59], 0
	v_mov_b64_e32 v[60:61], 0
	v_mov_b64_e32 v[62:63], 0
	v_mov_b64_e32 v[64:65], 0
	v_mov_b64_e32 v[66:67], 0
	v_mov_b64_e32 v[68:69], 0
	v_mov_b64_e32 v[70:71], 0
	v_mov_b64_e32 v[72:73], 0
	v_mov_b64_e32 v[74:75], 0
	v_mov_b64_e32 v[76:77], 0
	v_mov_b64_e32 v[78:79], 0
	v_mov_b64_e32 v[80:81], 0
	v_mov_b64_e32 v[82:83], 0
	v_mov_b64_e32 v[84:85], 0
	v_mov_b64_e32 v[86:87], 0
	v_mov_b64_e32 v[88:89], 0
	v_mov_b64_e32 v[90:91], 0
	v_mov_b64_e32 v[92:93], 0
	v_mov_b64_e32 v[94:95], 0
	v_mov_b64_e32 v[96:97], 0
	v_mov_b64_e32 v[98:99], 0
	v_mov_b64_e32 v[100:101], 0
	v_mov_b64_e32 v[102:103], 0
	v_mov_b64_e32 v[104:105], 0
	v_mov_b64_e32 v[106:107], 0
	v_mov_b64_e32 v[108:109], 0
	v_mov_b64_e32 v[110:111], 0
	v_mov_b64_e32 v[112:113], 0
	v_mov_b64_e32 v[114:115], 0
	v_mov_b64_e32 v[116:117], 0
	v_mov_b64_e32 v[118:119], 0
	v_mov_b64_e32 v[120:121], 0
	v_mov_b64_e32 v[122:123], 0
	v_mov_b64_e32 v[124:125], 0
	v_mov_b64_e32 v[126:127], 0
	s_addc_u32 s54, s31, 0
	s_mov_b32 s30, 0

.LBB0_427:
	s_add_u32 s34, s34, 0x40080
	s_addc_u32 s35, s35, 0
	s_add_u32 s15, s36, 0x100
	v_mov_b32_e32 v0, 0
	v_mov_b32_e32 v1, 0
	v_mov_b64_e32 v[2:3], 0
	v_mov_b64_e32 v[4:5], 0
	v_mov_b64_e32 v[6:7], 0
	v_mov_b64_e32 v[8:9], 0
	v_mov_b64_e32 v[10:11], 0
	v_mov_b64_e32 v[12:13], 0
	v_mov_b64_e32 v[14:15], 0
	v_mov_b64_e32 v[16:17], 0
	v_mov_b64_e32 v[18:19], 0
	v_mov_b64_e32 v[20:21], 0
	v_mov_b64_e32 v[22:23], 0
	v_mov_b64_e32 v[24:25], 0
	v_mov_b64_e32 v[26:27], 0
	v_mov_b64_e32 v[28:29], 0
	v_mov_b64_e32 v[30:31], 0
	v_mov_b64_e32 v[32:33], 0
	v_mov_b64_e32 v[34:35], 0
	v_mov_b64_e32 v[36:37], 0
	v_mov_b64_e32 v[38:39], 0
	v_mov_b64_e32 v[40:41], 0
	v_mov_b64_e32 v[42:43], 0
	v_mov_b64_e32 v[44:45], 0
	v_mov_b64_e32 v[46:47], 0
	v_mov_b64_e32 v[48:49], 0
	v_mov_b64_e32 v[50:51], 0
	v_mov_b64_e32 v[52:53], 0
	v_mov_b64_e32 v[54:55], 0
	v_mov_b64_e32 v[56:57], 0
	v_mov_b64_e32 v[58:59], 0
	v_mov_b64_e32 v[60:61], 0
	v_mov_b64_e32 v[62:63], 0
	v_mov_b64_e32 v[64:65], 0
	v_mov_b64_e32 v[66:67], 0
	v_mov_b64_e32 v[68:69], 0
	v_mov_b64_e32 v[70:71], 0
	v_mov_b64_e32 v[72:73], 0
	v_mov_b64_e32 v[74:75], 0
	v_mov_b64_e32 v[76:77], 0
	v_mov_b64_e32 v[78:79], 0
	v_mov_b64_e32 v[80:81], 0
	v_mov_b64_e32 v[82:83], 0
	v_mov_b64_e32 v[84:85], 0
	v_mov_b64_e32 v[86:87], 0
	v_mov_b64_e32 v[88:89], 0
	v_mov_b64_e32 v[90:91], 0
	v_mov_b64_e32 v[92:93], 0
	v_mov_b64_e32 v[94:95], 0
	v_mov_b64_e32 v[96:97], 0
	v_mov_b64_e32 v[98:99], 0
	v_mov_b64_e32 v[100:101], 0
	v_mov_b64_e32 v[102:103], 0
	v_mov_b64_e32 v[104:105], 0
	v_mov_b64_e32 v[106:107], 0
	v_mov_b64_e32 v[108:109], 0
	v_mov_b64_e32 v[110:111], 0
	v_mov_b64_e32 v[112:113], 0
	v_mov_b64_e32 v[114:115], 0
	v_mov_b64_e32 v[116:117], 0
	v_mov_b64_e32 v[118:119], 0
	v_mov_b64_e32 v[120:121], 0
	v_mov_b64_e32 v[122:123], 0
	v_mov_b64_e32 v[124:125], 0
	v_mov_b64_e32 v[126:127], 0
	s_addc_u32 s19, s37, 0
	s_mov_b32 s55, -2
	s_waitcnt lgkmcnt(0)
	s_waitcnt vmcnt(0)

.LBB0_513:
	s_add_u32 s36, s36, 0x40080
	s_addc_u32 s37, s37, 0
	s_add_u32 s21, s38, 0x100
	v_mov_b32_e32 v0, 0
	v_mov_b32_e32 v1, 0
	v_mov_b64_e32 v[2:3], 0
	v_mov_b64_e32 v[4:5], 0
	v_mov_b64_e32 v[6:7], 0
	v_mov_b64_e32 v[8:9], 0
	v_mov_b64_e32 v[10:11], 0
	v_mov_b64_e32 v[12:13], 0
	v_mov_b64_e32 v[14:15], 0
	v_mov_b64_e32 v[16:17], 0
	v_mov_b64_e32 v[18:19], 0
	v_mov_b64_e32 v[20:21], 0
	v_mov_b64_e32 v[22:23], 0
	v_mov_b64_e32 v[24:25], 0
	v_mov_b64_e32 v[26:27], 0
	v_mov_b64_e32 v[28:29], 0
	v_mov_b64_e32 v[30:31], 0
	v_mov_b64_e32 v[32:33], 0
	v_mov_b64_e32 v[34:35], 0
	v_mov_b64_e32 v[36:37], 0
	v_mov_b64_e32 v[38:39], 0
	v_mov_b64_e32 v[40:41], 0
	v_mov_b64_e32 v[42:43], 0
	v_mov_b64_e32 v[44:45], 0
	v_mov_b64_e32 v[46:47], 0
	v_mov_b64_e32 v[48:49], 0
	v_mov_b64_e32 v[50:51], 0
	v_mov_b64_e32 v[52:53], 0
	v_mov_b64_e32 v[54:55], 0
	v_mov_b64_e32 v[56:57], 0
	v_mov_b64_e32 v[58:59], 0
	v_mov_b64_e32 v[60:61], 0
	v_mov_b64_e32 v[62:63], 0
	v_mov_b64_e32 v[64:65], 0
	v_mov_b64_e32 v[66:67], 0
	v_mov_b64_e32 v[68:69], 0
	v_mov_b64_e32 v[70:71], 0
	v_mov_b64_e32 v[72:73], 0
	v_mov_b64_e32 v[74:75], 0
	v_mov_b64_e32 v[76:77], 0
	v_mov_b64_e32 v[78:79], 0
	v_mov_b64_e32 v[80:81], 0
	v_mov_b64_e32 v[82:83], 0
	v_mov_b64_e32 v[84:85], 0
	v_mov_b64_e32 v[86:87], 0
	v_mov_b64_e32 v[88:89], 0
	v_mov_b64_e32 v[90:91], 0
	v_mov_b64_e32 v[92:93], 0
	v_mov_b64_e32 v[94:95], 0
	v_mov_b64_e32 v[96:97], 0
	v_mov_b64_e32 v[98:99], 0
	v_mov_b64_e32 v[100:101], 0
	v_mov_b64_e32 v[102:103], 0
	v_mov_b64_e32 v[104:105], 0
	v_mov_b64_e32 v[106:107], 0
	v_mov_b64_e32 v[108:109], 0
	v_mov_b64_e32 v[110:111], 0
	v_mov_b64_e32 v[112:113], 0
	v_mov_b64_e32 v[114:115], 0
	v_mov_b64_e32 v[116:117], 0
	v_mov_b64_e32 v[118:119], 0
	v_mov_b64_e32 v[120:121], 0
	v_mov_b64_e32 v[122:123], 0
	v_mov_b64_e32 v[124:125], 0
	v_mov_b64_e32 v[126:127], 0
	s_addc_u32 s23, s39, 0
	s_mov_b32 s33, -2

.LBB0_602:
	s_add_u32 s38, s38, 0x40080
	s_addc_u32 s39, s39, 0
	s_add_u32 s29, s40, 0x100
	v_mov_b32_e32 v0, 0
	v_mov_b32_e32 v1, 0
	v_mov_b64_e32 v[2:3], 0
	v_mov_b64_e32 v[4:5], 0
	v_mov_b64_e32 v[6:7], 0
	v_mov_b64_e32 v[8:9], 0
	v_mov_b64_e32 v[10:11], 0
	v_mov_b64_e32 v[12:13], 0
	v_mov_b64_e32 v[14:15], 0
	v_mov_b64_e32 v[16:17], 0
	v_mov_b64_e32 v[18:19], 0
	v_mov_b64_e32 v[20:21], 0
	v_mov_b64_e32 v[22:23], 0
	v_mov_b64_e32 v[24:25], 0
	v_mov_b64_e32 v[26:27], 0
	v_mov_b64_e32 v[28:29], 0
	v_mov_b64_e32 v[30:31], 0
	v_mov_b64_e32 v[32:33], 0
	v_mov_b64_e32 v[34:35], 0
	v_mov_b64_e32 v[36:37], 0
	v_mov_b64_e32 v[38:39], 0
	v_mov_b64_e32 v[40:41], 0
	v_mov_b64_e32 v[42:43], 0
	v_mov_b64_e32 v[44:45], 0
	v_mov_b64_e32 v[46:47], 0
	v_mov_b64_e32 v[48:49], 0
	v_mov_b64_e32 v[50:51], 0
	v_mov_b64_e32 v[52:53], 0
	v_mov_b64_e32 v[54:55], 0
	v_mov_b64_e32 v[56:57], 0
	v_mov_b64_e32 v[58:59], 0
	v_mov_b64_e32 v[60:61], 0
	v_mov_b64_e32 v[62:63], 0
	v_mov_b64_e32 v[64:65], 0
	v_mov_b64_e32 v[66:67], 0
	v_mov_b64_e32 v[68:69], 0
	v_mov_b64_e32 v[70:71], 0
	v_mov_b64_e32 v[72:73], 0
	v_mov_b64_e32 v[74:75], 0
	v_mov_b64_e32 v[76:77], 0
	v_mov_b64_e32 v[78:79], 0
	v_mov_b64_e32 v[80:81], 0
	v_mov_b64_e32 v[82:83], 0
	v_mov_b64_e32 v[84:85], 0
	v_mov_b64_e32 v[86:87], 0
	v_mov_b64_e32 v[88:89], 0
	v_mov_b64_e32 v[90:91], 0
	v_mov_b64_e32 v[92:93], 0
	v_mov_b64_e32 v[94:95], 0
	v_mov_b64_e32 v[96:97], 0
	v_mov_b64_e32 v[98:99], 0
	v_mov_b64_e32 v[100:101], 0
	v_mov_b64_e32 v[102:103], 0
	v_mov_b64_e32 v[104:105], 0
	v_mov_b64_e32 v[106:107], 0
	v_mov_b64_e32 v[108:109], 0
	v_mov_b64_e32 v[110:111], 0
	v_mov_b64_e32 v[112:113], 0
	v_mov_b64_e32 v[114:115], 0
	v_mov_b64_e32 v[116:117], 0
	v_mov_b64_e32 v[118:119], 0
	v_mov_b64_e32 v[120:121], 0
	v_mov_b64_e32 v[122:123], 0
	v_mov_b64_e32 v[124:125], 0
	v_mov_b64_e32 v[126:127], 0
	s_addc_u32 s31, s41, 0
	s_mov_b32 s56, -2
	s_waitcnt lgkmcnt(0)

.LBB0_689:
	s_add_u32 s28, s28, 0x40080
	s_addc_u32 s29, s29, 0
	s_add_u32 s3, s30, 0x100
	v_mov_b32_e32 v0, 0
	v_mov_b32_e32 v1, 0
	v_mov_b64_e32 v[2:3], 0
	v_mov_b64_e32 v[4:5], 0
	v_mov_b64_e32 v[6:7], 0
	v_mov_b64_e32 v[8:9], 0
	v_mov_b64_e32 v[10:11], 0
	v_mov_b64_e32 v[12:13], 0
	v_mov_b64_e32 v[14:15], 0
	v_mov_b64_e32 v[16:17], 0
	v_mov_b64_e32 v[18:19], 0
	v_mov_b64_e32 v[20:21], 0
	v_mov_b64_e32 v[22:23], 0
	v_mov_b64_e32 v[24:25], 0
	v_mov_b64_e32 v[26:27], 0
	v_mov_b64_e32 v[28:29], 0
	v_mov_b64_e32 v[30:31], 0
	v_mov_b64_e32 v[32:33], 0
	v_mov_b64_e32 v[34:35], 0
	v_mov_b64_e32 v[36:37], 0
	v_mov_b64_e32 v[38:39], 0
	v_mov_b64_e32 v[40:41], 0
	v_mov_b64_e32 v[42:43], 0
	v_mov_b64_e32 v[44:45], 0
	v_mov_b64_e32 v[46:47], 0
	v_mov_b64_e32 v[48:49], 0
	v_mov_b64_e32 v[50:51], 0
	v_mov_b64_e32 v[52:53], 0
	v_mov_b64_e32 v[54:55], 0
	v_mov_b64_e32 v[56:57], 0
	v_mov_b64_e32 v[58:59], 0
	v_mov_b64_e32 v[60:61], 0
	v_mov_b64_e32 v[62:63], 0
	v_mov_b64_e32 v[64:65], 0
	v_mov_b64_e32 v[66:67], 0
	v_mov_b64_e32 v[68:69], 0
	v_mov_b64_e32 v[70:71], 0
	v_mov_b64_e32 v[72:73], 0
	v_mov_b64_e32 v[74:75], 0
	v_mov_b64_e32 v[76:77], 0
	v_mov_b64_e32 v[78:79], 0
	v_mov_b64_e32 v[80:81], 0
	v_mov_b64_e32 v[82:83], 0
	v_mov_b64_e32 v[84:85], 0
	v_mov_b64_e32 v[86:87], 0
	v_mov_b64_e32 v[88:89], 0
	v_mov_b64_e32 v[90:91], 0
	v_mov_b64_e32 v[92:93], 0
	v_mov_b64_e32 v[94:95], 0
	v_mov_b64_e32 v[96:97], 0
	v_mov_b64_e32 v[98:99], 0
	v_mov_b64_e32 v[100:101], 0
	v_mov_b64_e32 v[102:103], 0
	v_mov_b64_e32 v[104:105], 0
	v_mov_b64_e32 v[106:107], 0
	v_mov_b64_e32 v[108:109], 0
	v_mov_b64_e32 v[110:111], 0
	v_mov_b64_e32 v[112:113], 0
	v_mov_b64_e32 v[114:115], 0
	v_mov_b64_e32 v[116:117], 0
	v_mov_b64_e32 v[118:119], 0
	v_mov_b64_e32 v[120:121], 0
	v_mov_b64_e32 v[122:123], 0
	v_mov_b64_e32 v[124:125], 0
	v_mov_b64_e32 v[126:127], 0
	s_addc_u32 s17, s31, 0
	s_mov_b32 s51, -2

.LBB0_789:
	s_add_u32 s11, s40, 0x100
	s_addc_u32 s29, s41, 0
	s_add_u32 s38, s38, 0xc000
	v_mov_b32_e32 v0, 0
	v_mov_b32_e32 v1, 0
	v_mov_b64_e32 v[2:3], 0
	v_mov_b64_e32 v[4:5], 0
	v_mov_b64_e32 v[6:7], 0
	v_mov_b64_e32 v[8:9], 0
	v_mov_b64_e32 v[10:11], 0
	v_mov_b64_e32 v[12:13], 0
	v_mov_b64_e32 v[14:15], 0
	v_mov_b64_e32 v[16:17], 0
	v_mov_b64_e32 v[18:19], 0
	v_mov_b64_e32 v[20:21], 0
	v_mov_b64_e32 v[22:23], 0
	v_mov_b64_e32 v[24:25], 0
	v_mov_b64_e32 v[26:27], 0
	v_mov_b64_e32 v[28:29], 0
	v_mov_b64_e32 v[30:31], 0
	v_mov_b64_e32 v[32:33], 0
	v_mov_b64_e32 v[34:35], 0
	v_mov_b64_e32 v[36:37], 0
	v_mov_b64_e32 v[38:39], 0
	v_mov_b64_e32 v[40:41], 0
	v_mov_b64_e32 v[42:43], 0
	v_mov_b64_e32 v[44:45], 0
	v_mov_b64_e32 v[46:47], 0
	v_mov_b64_e32 v[48:49], 0
	v_mov_b64_e32 v[50:51], 0
	v_mov_b64_e32 v[52:53], 0
	v_mov_b64_e32 v[54:55], 0
	v_mov_b64_e32 v[56:57], 0
	v_mov_b64_e32 v[58:59], 0
	v_mov_b64_e32 v[60:61], 0
	v_mov_b64_e32 v[62:63], 0
	v_mov_b64_e32 v[64:65], 0
	v_mov_b64_e32 v[66:67], 0
	v_mov_b64_e32 v[68:69], 0
	v_mov_b64_e32 v[70:71], 0
	v_mov_b64_e32 v[72:73], 0
	v_mov_b64_e32 v[74:75], 0
	v_mov_b64_e32 v[76:77], 0
	v_mov_b64_e32 v[78:79], 0
	v_mov_b64_e32 v[80:81], 0
	v_mov_b64_e32 v[82:83], 0
	v_mov_b64_e32 v[84:85], 0
	v_mov_b64_e32 v[86:87], 0
	v_mov_b64_e32 v[88:89], 0
	v_mov_b64_e32 v[90:91], 0
	v_mov_b64_e32 v[92:93], 0
	v_mov_b64_e32 v[94:95], 0
	v_mov_b64_e32 v[96:97], 0
	v_mov_b64_e32 v[98:99], 0
	v_mov_b64_e32 v[100:101], 0
	v_mov_b64_e32 v[102:103], 0
	v_mov_b64_e32 v[104:105], 0
	v_mov_b64_e32 v[106:107], 0
	v_mov_b64_e32 v[108:109], 0
	v_mov_b64_e32 v[110:111], 0
	v_mov_b64_e32 v[112:113], 0
	v_mov_b64_e32 v[114:115], 0
	v_mov_b64_e32 v[116:117], 0
	v_mov_b64_e32 v[118:119], 0
	v_mov_b64_e32 v[120:121], 0
	v_mov_b64_e32 v[122:123], 0
	v_mov_b64_e32 v[124:125], 0
	v_mov_b64_e32 v[126:127], 0
	s_addc_u32 s39, s39, 0
	s_mov_b32 s33, -2
